# nine grid-barrier instances use a shorter protocol (XCD-local arrival count, one release per XCD, all blocks poll one word)
# speedup vs baseline: 1.2577x; 1.0050x over previous
; __device__ __forceinline__ unsigned xb_ld(unsigned* p)              { return __hip_atomic_load(p, __ATOMIC_RELAXED, __HIP_MEMORY_SCOPE_AGENT); }
; __device__ __forceinline__ unsigned xb_add(unsigned* p, unsigned v) { return __hip_atomic_fetch_add(p, v, __ATOMIC_RELAXED, __HIP_MEMORY_SCOPE_AGENT); }
; #define XB_SPIN(cond, bar) do { unsigned _sp = 0; while (cond) { __builtin_amdgcn_s_sleep(1); \
;     if ((++_sp & 255u) == 0u) { if (xb_ld(&(bar)[XB_TMO])) break; if (_sp > XB_SPIN_CAP) { atomicAdd(&(bar)[XB_TMO], 1u); break; } } } } while (0)
; __device__ __forceinline__ void xcd_barrier(const XcdBarrier& b) {
;   asm volatile("s_waitcnt vmcnt(0)" ::: "memory");
;   __syncthreads();
;   if (threadIdx.x == 0) {
;     unsigned* bar = b.bar;
;     __builtin_amdgcn_s_waitcnt(0);
;     unsigned nloc = b.st[0], nx = b.st[1];
;     if (nloc == 0u) { xcd_barrier_complete(bar, b.x, nloc, nx); b.st[0] = nloc; b.st[1] = nx; }
;     const unsigned old = xb_add(&bar[XB_XSUB(b.x)], 1u);
;     const unsigned gen = old / nloc;
;     if (old + 1u == (gen + 1u) * nloc) {
;       __builtin_amdgcn_fence(__ATOMIC_RELEASE, "agent");
;       asm volatile("s_waitcnt vmcnt(0)" ::: "memory");
;       const unsigned og = xb_add(&bar[XB_TOP], 1u);
;       const unsigned tg = og / nx;
;       if (og + 1u == (tg + 1u) * nx) xb_add(&bar[XB_TOPGEN], 1u);
;       else XB_SPIN(xb_ld(&bar[XB_TOPGEN]) == tg, bar);
;       __builtin_amdgcn_fence(__ATOMIC_ACQUIRE, "agent");
;       xb_add(&bar[XB_XGEN(b.x)], 1u);
;       asm volatile("s_waitcnt vmcnt(0)" ::: "memory");
;     } else {
;       XB_SPIN(xb_ld(&bar[XB_XGEN(b.x)]) == gen, bar);
;       __builtin_amdgcn_fence(__ATOMIC_ACQUIRE, "agent");
;       asm volatile("s_waitcnt vmcnt(0)" ::: "memory");
;     }
;   }
;   __syncthreads();
; }
.LBB0_259:
	s_waitcnt vmcnt(0)
	s_barrier
	s_cmp_eq_u64 s[38:39], 0
	s_cbranch_scc1 .Lfb0_done
	s_mov_b64 s[6:7], exec
	s_mov_b64 exec, s[38:39]
	ds_read_b32 v1, v145 offset:40968
	ds_read_b32 v6, v145 offset:40960
	ds_read_b32 v7, v145 offset:40964
	s_getreg_b32 s2, hwreg(HW_REG_XCC_ID, 0, 4)
	s_and_b32 s2, s2, 7
	s_lshl_b32 s2, s2, 8
	s_add_u32 s0, s74, 0x2500
	s_addc_u32 s1, s75, 0
	v_mov_b32_e32 v0, 1
	v_mov_b32_e32 v2, s2
	s_waitcnt vmcnt(0) lgkmcnt(0)
	global_atomic_add v4, v2, v0, s[0:1] offset:-128 sc0
	v_add_u32_e32 v1, 1, v1
	ds_write_b32 v145, v1 offset:40968
	v_mul_lo_u32 v6, v6, v1
	v_mul_lo_u32 v7, v7, v1
	s_waitcnt vmcnt(0)
	v_add_u32_e32 v4, 1, v4
	v_cmp_eq_u32_e32 vcc, v4, v6
	s_cbranch_vccz .Lfb0_poll
	buffer_wbl2 sc1
	s_waitcnt vmcnt(0)
	global_atomic_add v145, v0, s[0:1] offset:3968
.Lfb0_poll:
	s_mov_b32 s4, 0
.Lfb0_spin:
	global_load_dword v5, v145, s[0:1] offset:3968 sc1
	s_waitcnt vmcnt(0)
	v_cmp_ge_u32_e32 vcc, v5, v7
	s_cbranch_vccnz .Lfb0_out
	s_sleep 1
	s_add_u32 s4, s4, 1
	s_cmp_lt_u32 s4, 0x40000
	s_cbranch_scc1 .Lfb0_spin
.Lfb0_out:
	buffer_inv sc1
	s_waitcnt vmcnt(0) lgkmcnt(0)
	s_mov_b64 exec, s[6:7]
.Lfb0_done:
	s_and_saveexec_b64 s[22:23], s[38:39]
	v_readlane_b32 s18, v224, 26
	v_readlane_b32 s19, v224, 27
	s_branch .LBB0_311
	s_waitcnt vmcnt(0) expcnt(0) lgkmcnt(0)
	ds_read_b32 v2, v145 offset:40960
	ds_read_b32 v0, v145 offset:40964
	s_waitcnt lgkmcnt(1)
	v_cmp_ne_u32_e32 vcc, 0, v2
	s_cbranch_vccnz .LBB0_275
	s_mov_b32 s2, 1
	s_branch .LBB0_263

; __device__ __forceinline__ unsigned xb_ld(unsigned* p)              { return __hip_atomic_load(p, __ATOMIC_RELAXED, __HIP_MEMORY_SCOPE_AGENT); }
; __device__ __forceinline__ unsigned xb_add(unsigned* p, unsigned v) { return __hip_atomic_fetch_add(p, v, __ATOMIC_RELAXED, __HIP_MEMORY_SCOPE_AGENT); }
; #define XB_SPIN(cond, bar) do { unsigned _sp = 0; while (cond) { __builtin_amdgcn_s_sleep(1); \
;     if ((++_sp & 255u) == 0u) { if (xb_ld(&(bar)[XB_TMO])) break; if (_sp > XB_SPIN_CAP) { atomicAdd(&(bar)[XB_TMO], 1u); break; } } } } while (0)
; __device__ __forceinline__ void xcd_barrier(const XcdBarrier& b) {
;   asm volatile("s_waitcnt vmcnt(0)" ::: "memory");
;   __syncthreads();
;   if (threadIdx.x == 0) {
;     unsigned* bar = b.bar;
;     __builtin_amdgcn_s_waitcnt(0);
;     unsigned nloc = b.st[0], nx = b.st[1];
;     if (nloc == 0u) { xcd_barrier_complete(bar, b.x, nloc, nx); b.st[0] = nloc; b.st[1] = nx; }
;     const unsigned old = xb_add(&bar[XB_XSUB(b.x)], 1u);
;     const unsigned gen = old / nloc;
;     if (old + 1u == (gen + 1u) * nloc) {
;       __builtin_amdgcn_fence(__ATOMIC_RELEASE, "agent");
;       asm volatile("s_waitcnt vmcnt(0)" ::: "memory");
;       const unsigned og = xb_add(&bar[XB_TOP], 1u);
;       const unsigned tg = og / nx;
;       if (og + 1u == (tg + 1u) * nx) xb_add(&bar[XB_TOPGEN], 1u);
;       else XB_SPIN(xb_ld(&bar[XB_TOPGEN]) == tg, bar);
;       __builtin_amdgcn_fence(__ATOMIC_ACQUIRE, "agent");
;       xb_add(&bar[XB_XGEN(b.x)], 1u);
;       asm volatile("s_waitcnt vmcnt(0)" ::: "memory");
;     } else {
;       XB_SPIN(xb_ld(&bar[XB_XGEN(b.x)]) == gen, bar);
;       __builtin_amdgcn_fence(__ATOMIC_ACQUIRE, "agent");
;       asm volatile("s_waitcnt vmcnt(0)" ::: "memory");
;     }
;   }
;   __syncthreads();
; }
.Linpj_end:
.LBB0_324:
	s_waitcnt vmcnt(0)
	s_waitcnt vmcnt(63) expcnt(7) lgkmcnt(15)
	s_barrier
	s_cmp_eq_u64 s[38:39], 0
	s_cbranch_scc1 .Lfb1_done
	s_mov_b64 s[6:7], exec
	s_mov_b64 exec, s[38:39]
	ds_read_b32 v1, v145 offset:40968
	ds_read_b32 v6, v145 offset:40960
	ds_read_b32 v7, v145 offset:40964
	s_getreg_b32 s2, hwreg(HW_REG_XCC_ID, 0, 4)
	s_and_b32 s2, s2, 7
	s_lshl_b32 s2, s2, 8
	s_add_u32 s0, s74, 0x2500
	s_addc_u32 s1, s75, 0
	v_mov_b32_e32 v0, 1
	v_mov_b32_e32 v2, s2
	s_waitcnt vmcnt(0) lgkmcnt(0)
	global_atomic_add v4, v2, v0, s[0:1] offset:-128 sc0
	v_add_u32_e32 v1, 1, v1
	ds_write_b32 v145, v1 offset:40968
	v_mul_lo_u32 v6, v6, v1
	v_mul_lo_u32 v7, v7, v1
	s_waitcnt vmcnt(0)
	v_add_u32_e32 v4, 1, v4
	v_cmp_eq_u32_e32 vcc, v4, v6
	s_cbranch_vccz .Lfb1_poll
	buffer_wbl2 sc1
	s_waitcnt vmcnt(0)
	global_atomic_add v145, v0, s[0:1] offset:3968

; __device__ __forceinline__ unsigned xb_ld(unsigned* p)              { return __hip_atomic_load(p, __ATOMIC_RELAXED, __HIP_MEMORY_SCOPE_AGENT); }
; __device__ __forceinline__ unsigned xb_add(unsigned* p, unsigned v) { return __hip_atomic_fetch_add(p, v, __ATOMIC_RELAXED, __HIP_MEMORY_SCOPE_AGENT); }
; #define XB_SPIN(cond, bar) do { unsigned _sp = 0; while (cond) { __builtin_amdgcn_s_sleep(1); \
;     if ((++_sp & 255u) == 0u) { if (xb_ld(&(bar)[XB_TMO])) break; if (_sp > XB_SPIN_CAP) { atomicAdd(&(bar)[XB_TMO], 1u); break; } } } } while (0)
; __device__ __forceinline__ void xcd_barrier(const XcdBarrier& b) {
;   asm volatile("s_waitcnt vmcnt(0)" ::: "memory");
;   __syncthreads();
;   if (threadIdx.x == 0) {
;     unsigned* bar = b.bar;
;     __builtin_amdgcn_s_waitcnt(0);
;     unsigned nloc = b.st[0], nx = b.st[1];
;     if (nloc == 0u) { xcd_barrier_complete(bar, b.x, nloc, nx); b.st[0] = nloc; b.st[1] = nx; }
;     const unsigned old = xb_add(&bar[XB_XSUB(b.x)], 1u);
;     const unsigned gen = old / nloc;
;     if (old + 1u == (gen + 1u) * nloc) {
;       __builtin_amdgcn_fence(__ATOMIC_RELEASE, "agent");
;       asm volatile("s_waitcnt vmcnt(0)" ::: "memory");
;       const unsigned og = xb_add(&bar[XB_TOP], 1u);
;       const unsigned tg = og / nx;
;       if (og + 1u == (tg + 1u) * nx) xb_add(&bar[XB_TOPGEN], 1u);
;       else XB_SPIN(xb_ld(&bar[XB_TOPGEN]) == tg, bar);
;       __builtin_amdgcn_fence(__ATOMIC_ACQUIRE, "agent");
;       xb_add(&bar[XB_XGEN(b.x)], 1u);
;       asm volatile("s_waitcnt vmcnt(0)" ::: "memory");
;     } else {
;       XB_SPIN(xb_ld(&bar[XB_XGEN(b.x)]) == gen, bar);
;       __builtin_amdgcn_fence(__ATOMIC_ACQUIRE, "agent");
;       asm volatile("s_waitcnt vmcnt(0)" ::: "memory");
;     }
;   }
;   __syncthreads();
; }
.Lfb1_done:
	s_and_saveexec_b64 s[20:21], s[38:39]
	s_movk_i32 s0, 0x4000
	s_branch .LBB0_376
	s_waitcnt vmcnt(0) expcnt(0) lgkmcnt(0)
	ds_read_b32 v2, v145 offset:40960
	ds_read_b32 v0, v145 offset:40964
	s_waitcnt lgkmcnt(1)
	v_cmp_ne_u32_e32 vcc, 0, v2
	s_cbranch_vccnz .LBB0_340
	s_mov_b32 s2, 1
	s_branch .LBB0_328

; __device__ __forceinline__ unsigned xb_ld(unsigned* p)              { return __hip_atomic_load(p, __ATOMIC_RELAXED, __HIP_MEMORY_SCOPE_AGENT); }
; __device__ __forceinline__ unsigned xb_add(unsigned* p, unsigned v) { return __hip_atomic_fetch_add(p, v, __ATOMIC_RELAXED, __HIP_MEMORY_SCOPE_AGENT); }
; #define XB_SPIN(cond, bar) do { unsigned _sp = 0; while (cond) { __builtin_amdgcn_s_sleep(1); \
;     if ((++_sp & 255u) == 0u) { if (xb_ld(&(bar)[XB_TMO])) break; if (_sp > XB_SPIN_CAP) { atomicAdd(&(bar)[XB_TMO], 1u); break; } } } } while (0)
; __device__ __forceinline__ void xcd_barrier(const XcdBarrier& b) {
;   asm volatile("s_waitcnt vmcnt(0)" ::: "memory");
;   __syncthreads();
;   if (threadIdx.x == 0) {
;     unsigned* bar = b.bar;
;     __builtin_amdgcn_s_waitcnt(0);
;     unsigned nloc = b.st[0], nx = b.st[1];
;     if (nloc == 0u) { xcd_barrier_complete(bar, b.x, nloc, nx); b.st[0] = nloc; b.st[1] = nx; }
;     const unsigned old = xb_add(&bar[XB_XSUB(b.x)], 1u);
;     const unsigned gen = old / nloc;
;     if (old + 1u == (gen + 1u) * nloc) {
;       __builtin_amdgcn_fence(__ATOMIC_RELEASE, "agent");
;       asm volatile("s_waitcnt vmcnt(0)" ::: "memory");
;       const unsigned og = xb_add(&bar[XB_TOP], 1u);
;       const unsigned tg = og / nx;
;       if (og + 1u == (tg + 1u) * nx) xb_add(&bar[XB_TOPGEN], 1u);
;       else XB_SPIN(xb_ld(&bar[XB_TOPGEN]) == tg, bar);
;       __builtin_amdgcn_fence(__ATOMIC_ACQUIRE, "agent");
;       xb_add(&bar[XB_XGEN(b.x)], 1u);
;       asm volatile("s_waitcnt vmcnt(0)" ::: "memory");
;     } else {
;       XB_SPIN(xb_ld(&bar[XB_XGEN(b.x)]) == gen, bar);
;       __builtin_amdgcn_fence(__ATOMIC_ACQUIRE, "agent");
;       asm volatile("s_waitcnt vmcnt(0)" ::: "memory");
;     }
;   }
;   __syncthreads();
; }
.LBB0_389:
	s_waitcnt vmcnt(0)
	s_barrier
	s_cmp_eq_u64 s[38:39], 0
	s_cbranch_scc1 .Lfb2_done
	s_mov_b64 s[8:9], exec
	s_mov_b64 exec, s[38:39]
	ds_read_b32 v1, v145 offset:40968
	ds_read_b32 v6, v145 offset:40960
	ds_read_b32 v7, v145 offset:40964
	s_getreg_b32 s1, hwreg(HW_REG_XCC_ID, 0, 4)
	s_and_b32 s1, s1, 7
	s_lshl_b32 s1, s1, 8
	s_add_u32 s6, s74, 0x2500
	s_addc_u32 s7, s75, 0
	v_mov_b32_e32 v0, 1
	v_mov_b32_e32 v2, s1
	s_waitcnt vmcnt(0) lgkmcnt(0)
	global_atomic_add v4, v2, v0, s[6:7] offset:-128 sc0
	v_add_u32_e32 v1, 1, v1
	ds_write_b32 v145, v1 offset:40968
	v_mul_lo_u32 v6, v6, v1
	v_mul_lo_u32 v7, v7, v1
	s_waitcnt vmcnt(0)
	v_add_u32_e32 v4, 1, v4
	v_cmp_eq_u32_e32 vcc, v4, v6
	s_cbranch_vccz .Lfb2_poll
	buffer_wbl2 sc1
	s_waitcnt vmcnt(0)
	global_atomic_add v145, v0, s[6:7] offset:3968
.Lfb2_poll:
	s_mov_b32 s2, 0
.Lfb2_spin:
	global_load_dword v5, v145, s[6:7] offset:3968 sc1
	s_waitcnt vmcnt(0)
	v_cmp_ge_u32_e32 vcc, v5, v7
	s_cbranch_vccnz .Lfb2_out
	s_sleep 1
	s_add_u32 s2, s2, 1
	s_cmp_lt_u32 s2, 0x40000
	s_cbranch_scc1 .Lfb2_spin
.Lfb2_out:
	buffer_inv sc1
	s_waitcnt vmcnt(0) lgkmcnt(0)
	s_mov_b64 exec, s[8:9]
.Lfb2_done:
	s_and_saveexec_b64 s[20:21], s[38:39]
	v_readlane_b32 s8, v224, 24
	v_readlane_b32 s9, v224, 25
	s_movk_i32 s33, 0x1f8
	v_readlane_b32 s16, v224, 26
	v_readlane_b32 s17, v224, 27
	s_branch .LBB0_441
	s_waitcnt vmcnt(0) expcnt(0) lgkmcnt(0)
	ds_read_b32 v2, v145 offset:40960
	ds_read_b32 v0, v145 offset:40964
	s_waitcnt lgkmcnt(1)
	v_cmp_ne_u32_e32 vcc, 0, v2
	s_cbranch_vccnz .LBB0_405
	s_mov_b32 s2, 1
	s_branch .LBB0_393

; __device__ __forceinline__ unsigned xb_ld(unsigned* p)              { return __hip_atomic_load(p, __ATOMIC_RELAXED, __HIP_MEMORY_SCOPE_AGENT); }
; __device__ __forceinline__ unsigned xb_add(unsigned* p, unsigned v) { return __hip_atomic_fetch_add(p, v, __ATOMIC_RELAXED, __HIP_MEMORY_SCOPE_AGENT); }
; #define XB_SPIN(cond, bar) do { unsigned _sp = 0; while (cond) { __builtin_amdgcn_s_sleep(1); \
;     if ((++_sp & 255u) == 0u) { if (xb_ld(&(bar)[XB_TMO])) break; if (_sp > XB_SPIN_CAP) { atomicAdd(&(bar)[XB_TMO], 1u); break; } } } } while (0)
; __device__ __forceinline__ void xcd_barrier(const XcdBarrier& b) {
;   asm volatile("s_waitcnt vmcnt(0)" ::: "memory");
;   __syncthreads();
;   if (threadIdx.x == 0) {
;     unsigned* bar = b.bar;
;     __builtin_amdgcn_s_waitcnt(0);
;     unsigned nloc = b.st[0], nx = b.st[1];
;     if (nloc == 0u) { xcd_barrier_complete(bar, b.x, nloc, nx); b.st[0] = nloc; b.st[1] = nx; }
;     const unsigned old = xb_add(&bar[XB_XSUB(b.x)], 1u);
;     const unsigned gen = old / nloc;
;     if (old + 1u == (gen + 1u) * nloc) {
;       __builtin_amdgcn_fence(__ATOMIC_RELEASE, "agent");
;       asm volatile("s_waitcnt vmcnt(0)" ::: "memory");
;       const unsigned og = xb_add(&bar[XB_TOP], 1u);
;       const unsigned tg = og / nx;
;       if (og + 1u == (tg + 1u) * nx) xb_add(&bar[XB_TOPGEN], 1u);
;       else XB_SPIN(xb_ld(&bar[XB_TOPGEN]) == tg, bar);
;       __builtin_amdgcn_fence(__ATOMIC_ACQUIRE, "agent");
;       xb_add(&bar[XB_XGEN(b.x)], 1u);
;       asm volatile("s_waitcnt vmcnt(0)" ::: "memory");
;     } else {
;       XB_SPIN(xb_ld(&bar[XB_XGEN(b.x)]) == gen, bar);
;       __builtin_amdgcn_fence(__ATOMIC_ACQUIRE, "agent");
;       asm volatile("s_waitcnt vmcnt(0)" ::: "memory");
;     }
;   }
;   __syncthreads();
; }
.LBB0_767:
	s_waitcnt vmcnt(0)
	v_readlane_b32 s38, v225, 2
	s_mov_b32 s0, 0x8000
	v_readlane_b32 s39, v225, 3
	s_waitcnt vmcnt(63) expcnt(7) lgkmcnt(15)
	s_barrier
	s_cmp_eq_u64 s[38:39], 0
	s_cbranch_scc1 .Lfb3_done
	s_mov_b64 s[8:9], exec
	s_mov_b64 exec, s[38:39]
	ds_read_b32 v1, v145 offset:40968
	ds_read_b32 v6, v145 offset:40960
	ds_read_b32 v7, v145 offset:40964
	s_getreg_b32 s1, hwreg(HW_REG_XCC_ID, 0, 4)
	s_and_b32 s1, s1, 7
	s_lshl_b32 s1, s1, 8
	s_add_u32 s6, s74, 0x2500
	s_addc_u32 s7, s75, 0
	v_mov_b32_e32 v0, 1
	v_mov_b32_e32 v2, s1
	s_waitcnt vmcnt(0) lgkmcnt(0)
	global_atomic_add v4, v2, v0, s[6:7] offset:-128 sc0
	v_add_u32_e32 v1, 1, v1
	ds_write_b32 v145, v1 offset:40968
	v_mul_lo_u32 v6, v6, v1
	v_mul_lo_u32 v7, v7, v1
	s_waitcnt vmcnt(0)
	v_add_u32_e32 v4, 1, v4
	v_cmp_eq_u32_e32 vcc, v4, v6
	s_cbranch_vccz .Lfb3_poll
	buffer_wbl2 sc1
	s_waitcnt vmcnt(0)
	global_atomic_add v145, v0, s[6:7] offset:3968

; __device__ __forceinline__ unsigned xb_ld(unsigned* p)              { return __hip_atomic_load(p, __ATOMIC_RELAXED, __HIP_MEMORY_SCOPE_AGENT); }
; __device__ __forceinline__ unsigned xb_add(unsigned* p, unsigned v) { return __hip_atomic_fetch_add(p, v, __ATOMIC_RELAXED, __HIP_MEMORY_SCOPE_AGENT); }
; #define XB_SPIN(cond, bar) do { unsigned _sp = 0; while (cond) { __builtin_amdgcn_s_sleep(1); \
;     if ((++_sp & 255u) == 0u) { if (xb_ld(&(bar)[XB_TMO])) break; if (_sp > XB_SPIN_CAP) { atomicAdd(&(bar)[XB_TMO], 1u); break; } } } } while (0)
; __device__ __forceinline__ void xcd_barrier(const XcdBarrier& b) {
;   asm volatile("s_waitcnt vmcnt(0)" ::: "memory");
;   __syncthreads();
;   if (threadIdx.x == 0) {
;     unsigned* bar = b.bar;
;     __builtin_amdgcn_s_waitcnt(0);
;     unsigned nloc = b.st[0], nx = b.st[1];
;     if (nloc == 0u) { xcd_barrier_complete(bar, b.x, nloc, nx); b.st[0] = nloc; b.st[1] = nx; }
;     const unsigned old = xb_add(&bar[XB_XSUB(b.x)], 1u);
;     const unsigned gen = old / nloc;
;     if (old + 1u == (gen + 1u) * nloc) {
;       __builtin_amdgcn_fence(__ATOMIC_RELEASE, "agent");
;       asm volatile("s_waitcnt vmcnt(0)" ::: "memory");
;       const unsigned og = xb_add(&bar[XB_TOP], 1u);
;       const unsigned tg = og / nx;
;       if (og + 1u == (tg + 1u) * nx) xb_add(&bar[XB_TOPGEN], 1u);
;       else XB_SPIN(xb_ld(&bar[XB_TOPGEN]) == tg, bar);
;       __builtin_amdgcn_fence(__ATOMIC_ACQUIRE, "agent");
;       xb_add(&bar[XB_XGEN(b.x)], 1u);
;       asm volatile("s_waitcnt vmcnt(0)" ::: "memory");
;     } else {
;       XB_SPIN(xb_ld(&bar[XB_XGEN(b.x)]) == gen, bar);
;       __builtin_amdgcn_fence(__ATOMIC_ACQUIRE, "agent");
;       asm volatile("s_waitcnt vmcnt(0)" ::: "memory");
;     }
;   }
;   __syncthreads();
; }
.Lfb3_done:
	s_and_saveexec_b64 s[20:21], s[38:39]
	v_readlane_b32 s64, v224, 20
	v_readlane_b32 s66, v224, 22
	v_readlane_b32 s60, v224, 24
	v_readlane_b32 s16, v224, 30
	v_readlane_b32 s50, v224, 26
	v_readlane_b32 s33, v225, 4
	v_readlane_b32 s65, v224, 21
	v_readlane_b32 s67, v224, 23
	v_readlane_b32 s61, v224, 25
	v_readlane_b32 s17, v224, 31
	v_readlane_b32 s51, v224, 27
	s_branch .LBB0_819
	s_waitcnt vmcnt(0) expcnt(0) lgkmcnt(0)
	ds_read_b32 v2, v145 offset:40960
	ds_read_b32 v0, v145 offset:40964
	s_waitcnt lgkmcnt(1)
	v_cmp_ne_u32_e32 vcc, 0, v2
	s_cbranch_vccnz .LBB0_783
	s_mov_b32 s2, 1
	s_branch .LBB0_771

; __device__ __forceinline__ unsigned xb_ld(unsigned* p)              { return __hip_atomic_load(p, __ATOMIC_RELAXED, __HIP_MEMORY_SCOPE_AGENT); }
; __device__ __forceinline__ unsigned xb_add(unsigned* p, unsigned v) { return __hip_atomic_fetch_add(p, v, __ATOMIC_RELAXED, __HIP_MEMORY_SCOPE_AGENT); }
; #define XB_SPIN(cond, bar) do { unsigned _sp = 0; while (cond) { __builtin_amdgcn_s_sleep(1); \
;     if ((++_sp & 255u) == 0u) { if (xb_ld(&(bar)[XB_TMO])) break; if (_sp > XB_SPIN_CAP) { atomicAdd(&(bar)[XB_TMO], 1u); break; } } } } while (0)
; __device__ __forceinline__ void xcd_barrier(const XcdBarrier& b) {
;   asm volatile("s_waitcnt vmcnt(0)" ::: "memory");
;   __syncthreads();
;   if (threadIdx.x == 0) {
;     unsigned* bar = b.bar;
;     __builtin_amdgcn_s_waitcnt(0);
;     unsigned nloc = b.st[0], nx = b.st[1];
;     if (nloc == 0u) { xcd_barrier_complete(bar, b.x, nloc, nx); b.st[0] = nloc; b.st[1] = nx; }
;     const unsigned old = xb_add(&bar[XB_XSUB(b.x)], 1u);
;     const unsigned gen = old / nloc;
;     if (old + 1u == (gen + 1u) * nloc) {
;       __builtin_amdgcn_fence(__ATOMIC_RELEASE, "agent");
;       asm volatile("s_waitcnt vmcnt(0)" ::: "memory");
;       const unsigned og = xb_add(&bar[XB_TOP], 1u);
;       const unsigned tg = og / nx;
;       if (og + 1u == (tg + 1u) * nx) xb_add(&bar[XB_TOPGEN], 1u);
;       else XB_SPIN(xb_ld(&bar[XB_TOPGEN]) == tg, bar);
;       __builtin_amdgcn_fence(__ATOMIC_ACQUIRE, "agent");
;       xb_add(&bar[XB_XGEN(b.x)], 1u);
;       asm volatile("s_waitcnt vmcnt(0)" ::: "memory");
;     } else {
;       XB_SPIN(xb_ld(&bar[XB_XGEN(b.x)]) == gen, bar);
;       __builtin_amdgcn_fence(__ATOMIC_ACQUIRE, "agent");
;       asm volatile("s_waitcnt vmcnt(0)" ::: "memory");
;     }
;   }
;   __syncthreads();
; }
.LBB0_826:
	s_waitcnt vmcnt(0)
	s_waitcnt vmcnt(63) expcnt(7) lgkmcnt(15)
	s_barrier
	s_cmp_eq_u64 s[38:39], 0
	s_cbranch_scc1 .Lfb4_done
	s_mov_b64 s[8:9], exec
	s_mov_b64 exec, s[38:39]
	ds_read_b32 v1, v145 offset:40968
	ds_read_b32 v6, v145 offset:40960
	ds_read_b32 v7, v145 offset:40964
	s_getreg_b32 s1, hwreg(HW_REG_XCC_ID, 0, 4)
	s_and_b32 s1, s1, 7
	s_lshl_b32 s1, s1, 8
	s_add_u32 s6, s74, 0x2500
	s_addc_u32 s7, s75, 0
	v_mov_b32_e32 v0, 1
	v_mov_b32_e32 v2, s1
	s_waitcnt vmcnt(0) lgkmcnt(0)
	global_atomic_add v4, v2, v0, s[6:7] offset:-128 sc0
	v_add_u32_e32 v1, 1, v1
	ds_write_b32 v145, v1 offset:40968
	v_mul_lo_u32 v6, v6, v1
	v_mul_lo_u32 v7, v7, v1
	s_waitcnt vmcnt(0)
	v_add_u32_e32 v4, 1, v4
	v_cmp_eq_u32_e32 vcc, v4, v6
	s_cbranch_vccz .Lfb4_poll
	buffer_wbl2 sc1
	s_waitcnt vmcnt(0)
	global_atomic_add v145, v0, s[6:7] offset:3968

; __device__ __forceinline__ unsigned xb_ld(unsigned* p)              { return __hip_atomic_load(p, __ATOMIC_RELAXED, __HIP_MEMORY_SCOPE_AGENT); }
; __device__ __forceinline__ unsigned xb_add(unsigned* p, unsigned v) { return __hip_atomic_fetch_add(p, v, __ATOMIC_RELAXED, __HIP_MEMORY_SCOPE_AGENT); }
; #define XB_SPIN(cond, bar) do { unsigned _sp = 0; while (cond) { __builtin_amdgcn_s_sleep(1); \
;     if ((++_sp & 255u) == 0u) { if (xb_ld(&(bar)[XB_TMO])) break; if (_sp > XB_SPIN_CAP) { atomicAdd(&(bar)[XB_TMO], 1u); break; } } } } while (0)
; __device__ __forceinline__ void xcd_barrier(const XcdBarrier& b) {
;   asm volatile("s_waitcnt vmcnt(0)" ::: "memory");
;   __syncthreads();
;   if (threadIdx.x == 0) {
;     unsigned* bar = b.bar;
;     __builtin_amdgcn_s_waitcnt(0);
;     unsigned nloc = b.st[0], nx = b.st[1];
;     if (nloc == 0u) { xcd_barrier_complete(bar, b.x, nloc, nx); b.st[0] = nloc; b.st[1] = nx; }
;     const unsigned old = xb_add(&bar[XB_XSUB(b.x)], 1u);
;     const unsigned gen = old / nloc;
;     if (old + 1u == (gen + 1u) * nloc) {
;       __builtin_amdgcn_fence(__ATOMIC_RELEASE, "agent");
;       asm volatile("s_waitcnt vmcnt(0)" ::: "memory");
;       const unsigned og = xb_add(&bar[XB_TOP], 1u);
;       const unsigned tg = og / nx;
;       if (og + 1u == (tg + 1u) * nx) xb_add(&bar[XB_TOPGEN], 1u);
;       else XB_SPIN(xb_ld(&bar[XB_TOPGEN]) == tg, bar);
;       __builtin_amdgcn_fence(__ATOMIC_ACQUIRE, "agent");
;       xb_add(&bar[XB_XGEN(b.x)], 1u);
;       asm volatile("s_waitcnt vmcnt(0)" ::: "memory");
;     } else {
;       XB_SPIN(xb_ld(&bar[XB_XGEN(b.x)]) == gen, bar);
;       __builtin_amdgcn_fence(__ATOMIC_ACQUIRE, "agent");
;       asm volatile("s_waitcnt vmcnt(0)" ::: "memory");
;     }
;   }
;   __syncthreads();
; }
.Lfb4_done:
	s_and_saveexec_b64 s[20:21], s[38:39]
	s_movk_i32 s10, 0x80
	s_branch .LBB0_878
	s_waitcnt vmcnt(0) expcnt(0) lgkmcnt(0)
	ds_read_b32 v2, v145 offset:40960
	ds_read_b32 v0, v145 offset:40964
	s_waitcnt lgkmcnt(1)
	v_cmp_ne_u32_e32 vcc, 0, v2
	s_cbranch_vccnz .LBB0_842
	s_mov_b32 s2, 1
	s_branch .LBB0_830

; __device__ __forceinline__ unsigned xb_ld(unsigned* p)              { return __hip_atomic_load(p, __ATOMIC_RELAXED, __HIP_MEMORY_SCOPE_AGENT); }
; __device__ __forceinline__ unsigned xb_add(unsigned* p, unsigned v) { return __hip_atomic_fetch_add(p, v, __ATOMIC_RELAXED, __HIP_MEMORY_SCOPE_AGENT); }
; #define XB_SPIN(cond, bar) do { unsigned _sp = 0; while (cond) { __builtin_amdgcn_s_sleep(1); \
;     if ((++_sp & 255u) == 0u) { if (xb_ld(&(bar)[XB_TMO])) break; if (_sp > XB_SPIN_CAP) { atomicAdd(&(bar)[XB_TMO], 1u); break; } } } } while (0)
; __device__ __forceinline__ void xcd_barrier(const XcdBarrier& b) {
;   asm volatile("s_waitcnt vmcnt(0)" ::: "memory");
;   __syncthreads();
;   if (threadIdx.x == 0) {
;     unsigned* bar = b.bar;
;     __builtin_amdgcn_s_waitcnt(0);
;     unsigned nloc = b.st[0], nx = b.st[1];
;     if (nloc == 0u) { xcd_barrier_complete(bar, b.x, nloc, nx); b.st[0] = nloc; b.st[1] = nx; }
;     const unsigned old = xb_add(&bar[XB_XSUB(b.x)], 1u);
;     const unsigned gen = old / nloc;
;     if (old + 1u == (gen + 1u) * nloc) {
;       __builtin_amdgcn_fence(__ATOMIC_RELEASE, "agent");
;       asm volatile("s_waitcnt vmcnt(0)" ::: "memory");
;       const unsigned og = xb_add(&bar[XB_TOP], 1u);
;       const unsigned tg = og / nx;
;       if (og + 1u == (tg + 1u) * nx) xb_add(&bar[XB_TOPGEN], 1u);
;       else XB_SPIN(xb_ld(&bar[XB_TOPGEN]) == tg, bar);
;       __builtin_amdgcn_fence(__ATOMIC_ACQUIRE, "agent");
;       xb_add(&bar[XB_XGEN(b.x)], 1u);
;       asm volatile("s_waitcnt vmcnt(0)" ::: "memory");
;     } else {
;       XB_SPIN(xb_ld(&bar[XB_XGEN(b.x)]) == gen, bar);
;       __builtin_amdgcn_fence(__ATOMIC_ACQUIRE, "agent");
;       asm volatile("s_waitcnt vmcnt(0)" ::: "memory");
;     }
;   }
;   __syncthreads();
; }
.LBB0_894:
	s_waitcnt vmcnt(0)
	s_waitcnt vmcnt(63) expcnt(7) lgkmcnt(15)
	s_barrier
	s_cmp_eq_u64 s[38:39], 0
	s_cbranch_scc1 .Lfb5_done
	s_mov_b64 s[8:9], exec
	s_mov_b64 exec, s[38:39]
	ds_read_b32 v1, v145 offset:40968
	ds_read_b32 v6, v145 offset:40960
	ds_read_b32 v7, v145 offset:40964
	s_getreg_b32 s2, hwreg(HW_REG_XCC_ID, 0, 4)
	s_and_b32 s2, s2, 7
	s_lshl_b32 s2, s2, 8
	s_add_u32 s6, s74, 0x2500
	s_addc_u32 s7, s75, 0
	v_mov_b32_e32 v0, 1
	v_mov_b32_e32 v2, s2
	s_waitcnt vmcnt(0) lgkmcnt(0)
	global_atomic_add v4, v2, v0, s[6:7] offset:-128 sc0
	v_add_u32_e32 v1, 1, v1
	ds_write_b32 v145, v1 offset:40968
	v_mul_lo_u32 v6, v6, v1
	v_mul_lo_u32 v7, v7, v1
	s_waitcnt vmcnt(0)
	v_add_u32_e32 v4, 1, v4
	v_cmp_eq_u32_e32 vcc, v4, v6
	s_cbranch_vccz .Lfb5_poll
	buffer_wbl2 sc1
	s_waitcnt vmcnt(0)
	global_atomic_add v145, v0, s[6:7] offset:3968

; __device__ __forceinline__ unsigned xb_ld(unsigned* p)              { return __hip_atomic_load(p, __ATOMIC_RELAXED, __HIP_MEMORY_SCOPE_AGENT); }
; __device__ __forceinline__ unsigned xb_add(unsigned* p, unsigned v) { return __hip_atomic_fetch_add(p, v, __ATOMIC_RELAXED, __HIP_MEMORY_SCOPE_AGENT); }
; #define XB_SPIN(cond, bar) do { unsigned _sp = 0; while (cond) { __builtin_amdgcn_s_sleep(1); \
;     if ((++_sp & 255u) == 0u) { if (xb_ld(&(bar)[XB_TMO])) break; if (_sp > XB_SPIN_CAP) { atomicAdd(&(bar)[XB_TMO], 1u); break; } } } } while (0)
; __device__ __forceinline__ void xcd_barrier(const XcdBarrier& b) {
;   asm volatile("s_waitcnt vmcnt(0)" ::: "memory");
;   __syncthreads();
;   if (threadIdx.x == 0) {
;     unsigned* bar = b.bar;
;     __builtin_amdgcn_s_waitcnt(0);
;     unsigned nloc = b.st[0], nx = b.st[1];
;     if (nloc == 0u) { xcd_barrier_complete(bar, b.x, nloc, nx); b.st[0] = nloc; b.st[1] = nx; }
;     const unsigned old = xb_add(&bar[XB_XSUB(b.x)], 1u);
;     const unsigned gen = old / nloc;
;     if (old + 1u == (gen + 1u) * nloc) {
;       __builtin_amdgcn_fence(__ATOMIC_RELEASE, "agent");
;       asm volatile("s_waitcnt vmcnt(0)" ::: "memory");
;       const unsigned og = xb_add(&bar[XB_TOP], 1u);
;       const unsigned tg = og / nx;
;       if (og + 1u == (tg + 1u) * nx) xb_add(&bar[XB_TOPGEN], 1u);
;       else XB_SPIN(xb_ld(&bar[XB_TOPGEN]) == tg, bar);
;       __builtin_amdgcn_fence(__ATOMIC_ACQUIRE, "agent");
;       xb_add(&bar[XB_XGEN(b.x)], 1u);
;       asm volatile("s_waitcnt vmcnt(0)" ::: "memory");
;     } else {
;       XB_SPIN(xb_ld(&bar[XB_XGEN(b.x)]) == gen, bar);
;       __builtin_amdgcn_fence(__ATOMIC_ACQUIRE, "agent");
;       asm volatile("s_waitcnt vmcnt(0)" ::: "memory");
;     }
;   }
;   __syncthreads();
; }
.Lfb5_spin:
	global_load_dword v5, v145, s[6:7] offset:3968 sc1
	s_waitcnt vmcnt(0)
	v_cmp_ge_u32_e32 vcc, v5, v7
	s_cbranch_vccnz .Lfb5_out
	s_sleep 1
	s_add_u32 s4, s4, 1
	s_cmp_lt_u32 s4, 0x40000
	s_cbranch_scc1 .Lfb5_spin

; __device__ __forceinline__ unsigned xb_ld(unsigned* p)              { return __hip_atomic_load(p, __ATOMIC_RELAXED, __HIP_MEMORY_SCOPE_AGENT); }
; __device__ __forceinline__ unsigned xb_add(unsigned* p, unsigned v) { return __hip_atomic_fetch_add(p, v, __ATOMIC_RELAXED, __HIP_MEMORY_SCOPE_AGENT); }
; #define XB_SPIN(cond, bar) do { unsigned _sp = 0; while (cond) { __builtin_amdgcn_s_sleep(1); \
;     if ((++_sp & 255u) == 0u) { if (xb_ld(&(bar)[XB_TMO])) break; if (_sp > XB_SPIN_CAP) { atomicAdd(&(bar)[XB_TMO], 1u); break; } } } } while (0)
; __device__ __forceinline__ void xcd_barrier(const XcdBarrier& b) {
;   asm volatile("s_waitcnt vmcnt(0)" ::: "memory");
;   __syncthreads();
;   if (threadIdx.x == 0) {
;     unsigned* bar = b.bar;
;     __builtin_amdgcn_s_waitcnt(0);
;     unsigned nloc = b.st[0], nx = b.st[1];
;     if (nloc == 0u) { xcd_barrier_complete(bar, b.x, nloc, nx); b.st[0] = nloc; b.st[1] = nx; }
;     const unsigned old = xb_add(&bar[XB_XSUB(b.x)], 1u);
;     const unsigned gen = old / nloc;
;     if (old + 1u == (gen + 1u) * nloc) {
;       __builtin_amdgcn_fence(__ATOMIC_RELEASE, "agent");
;       asm volatile("s_waitcnt vmcnt(0)" ::: "memory");
;       const unsigned og = xb_add(&bar[XB_TOP], 1u);
;       const unsigned tg = og / nx;
;       if (og + 1u == (tg + 1u) * nx) xb_add(&bar[XB_TOPGEN], 1u);
;       else XB_SPIN(xb_ld(&bar[XB_TOPGEN]) == tg, bar);
;       __builtin_amdgcn_fence(__ATOMIC_ACQUIRE, "agent");
;       xb_add(&bar[XB_XGEN(b.x)], 1u);
;       asm volatile("s_waitcnt vmcnt(0)" ::: "memory");
;     } else {
;       XB_SPIN(xb_ld(&bar[XB_XGEN(b.x)]) == gen, bar);
;       __builtin_amdgcn_fence(__ATOMIC_ACQUIRE, "agent");
;       asm volatile("s_waitcnt vmcnt(0)" ::: "memory");
;     }
;   }
;   __syncthreads();
; }
.Lfb5_done:
	s_and_saveexec_b64 s[22:23], s[38:39]
	s_branch .LBB0_946
	s_waitcnt vmcnt(0) expcnt(0) lgkmcnt(0)
	ds_read_b32 v2, v145 offset:40960
	ds_read_b32 v0, v145 offset:40964
	s_waitcnt lgkmcnt(1)
	v_cmp_ne_u32_e32 vcc, 0, v2
	s_cbranch_vccnz .LBB0_910
	s_mov_b32 s2, 1
	s_branch .LBB0_898

; __device__ __forceinline__ unsigned xb_ld(unsigned* p)              { return __hip_atomic_load(p, __ATOMIC_RELAXED, __HIP_MEMORY_SCOPE_AGENT); }
; __device__ __forceinline__ unsigned xb_add(unsigned* p, unsigned v) { return __hip_atomic_fetch_add(p, v, __ATOMIC_RELAXED, __HIP_MEMORY_SCOPE_AGENT); }
; #define XB_SPIN(cond, bar) do { unsigned _sp = 0; while (cond) { __builtin_amdgcn_s_sleep(1); \
;     if ((++_sp & 255u) == 0u) { if (xb_ld(&(bar)[XB_TMO])) break; if (_sp > XB_SPIN_CAP) { atomicAdd(&(bar)[XB_TMO], 1u); break; } } } } while (0)
; __device__ __forceinline__ void xcd_barrier(const XcdBarrier& b) {
;   asm volatile("s_waitcnt vmcnt(0)" ::: "memory");
;   __syncthreads();
;   if (threadIdx.x == 0) {
;     unsigned* bar = b.bar;
;     __builtin_amdgcn_s_waitcnt(0);
;     unsigned nloc = b.st[0], nx = b.st[1];
;     if (nloc == 0u) { xcd_barrier_complete(bar, b.x, nloc, nx); b.st[0] = nloc; b.st[1] = nx; }
;     const unsigned old = xb_add(&bar[XB_XSUB(b.x)], 1u);
;     const unsigned gen = old / nloc;
;     if (old + 1u == (gen + 1u) * nloc) {
;       __builtin_amdgcn_fence(__ATOMIC_RELEASE, "agent");
;       asm volatile("s_waitcnt vmcnt(0)" ::: "memory");
;       const unsigned og = xb_add(&bar[XB_TOP], 1u);
;       const unsigned tg = og / nx;
;       if (og + 1u == (tg + 1u) * nx) xb_add(&bar[XB_TOPGEN], 1u);
;       else XB_SPIN(xb_ld(&bar[XB_TOPGEN]) == tg, bar);
;       __builtin_amdgcn_fence(__ATOMIC_ACQUIRE, "agent");
;       xb_add(&bar[XB_XGEN(b.x)], 1u);
;       asm volatile("s_waitcnt vmcnt(0)" ::: "memory");
;     } else {
;       XB_SPIN(xb_ld(&bar[XB_XGEN(b.x)]) == gen, bar);
;       __builtin_amdgcn_fence(__ATOMIC_ACQUIRE, "agent");
;       asm volatile("s_waitcnt vmcnt(0)" ::: "memory");
;     }
;   }
;   __syncthreads();
; }
.Lfb7_done:
	s_and_saveexec_b64 s[22:23], s[38:39]
	v_readlane_b32 s0, v224, 26
	v_readlane_b32 s1, v224, 27
	s_branch .LBB0_1064
	s_waitcnt vmcnt(0) expcnt(0) lgkmcnt(0)
	ds_read_b32 v2, v145 offset:40960
	ds_read_b32 v0, v145 offset:40964
	s_waitcnt lgkmcnt(1)
	v_cmp_ne_u32_e32 vcc, 0, v2
	s_cbranch_vccnz .LBB0_1028
	s_mov_b32 s2, 1
	s_branch .LBB0_1016

; __device__ __forceinline__ unsigned xb_ld(unsigned* p)              { return __hip_atomic_load(p, __ATOMIC_RELAXED, __HIP_MEMORY_SCOPE_AGENT); }
; __device__ __forceinline__ unsigned xb_add(unsigned* p, unsigned v) { return __hip_atomic_fetch_add(p, v, __ATOMIC_RELAXED, __HIP_MEMORY_SCOPE_AGENT); }
; #define XB_SPIN(cond, bar) do { unsigned _sp = 0; while (cond) { __builtin_amdgcn_s_sleep(1); \
;     if ((++_sp & 255u) == 0u) { if (xb_ld(&(bar)[XB_TMO])) break; if (_sp > XB_SPIN_CAP) { atomicAdd(&(bar)[XB_TMO], 1u); break; } } } } while (0)
; __device__ __forceinline__ void xcd_barrier(const XcdBarrier& b) {
;   asm volatile("s_waitcnt vmcnt(0)" ::: "memory");
;   __syncthreads();
;   if (threadIdx.x == 0) {
;     unsigned* bar = b.bar;
;     __builtin_amdgcn_s_waitcnt(0);
;     unsigned nloc = b.st[0], nx = b.st[1];
;     if (nloc == 0u) { xcd_barrier_complete(bar, b.x, nloc, nx); b.st[0] = nloc; b.st[1] = nx; }
;     const unsigned old = xb_add(&bar[XB_XSUB(b.x)], 1u);
;     const unsigned gen = old / nloc;
;     if (old + 1u == (gen + 1u) * nloc) {
;       __builtin_amdgcn_fence(__ATOMIC_RELEASE, "agent");
;       asm volatile("s_waitcnt vmcnt(0)" ::: "memory");
;       const unsigned og = xb_add(&bar[XB_TOP], 1u);
;       const unsigned tg = og / nx;
;       if (og + 1u == (tg + 1u) * nx) xb_add(&bar[XB_TOPGEN], 1u);
;       else XB_SPIN(xb_ld(&bar[XB_TOPGEN]) == tg, bar);
;       __builtin_amdgcn_fence(__ATOMIC_ACQUIRE, "agent");
;       xb_add(&bar[XB_XGEN(b.x)], 1u);
;       asm volatile("s_waitcnt vmcnt(0)" ::: "memory");
;     } else {
;       XB_SPIN(xb_ld(&bar[XB_XGEN(b.x)]) == gen, bar);
;       __builtin_amdgcn_fence(__ATOMIC_ACQUIRE, "agent");
;       asm volatile("s_waitcnt vmcnt(0)" ::: "memory");
;     }
;   }
;   __syncthreads();
; }
.LBB0_1075:
	s_waitcnt vmcnt(0)
	s_waitcnt vmcnt(63) expcnt(7) lgkmcnt(15)
	s_barrier
	s_cmp_eq_u64 s[38:39], 0
	s_cbranch_scc1 .Lfb8_done
	s_mov_b64 s[12:13], exec
	s_mov_b64 exec, s[38:39]
	ds_read_b32 v1, v145 offset:40968
	ds_read_b32 v6, v145 offset:40960
	ds_read_b32 v7, v145 offset:40964
	s_getreg_b32 s0, hwreg(HW_REG_XCC_ID, 0, 4)
	s_and_b32 s0, s0, 7
	s_lshl_b32 s0, s0, 8
	s_add_u32 s6, s74, 0x2500
	s_addc_u32 s7, s75, 0
	v_mov_b32_e32 v0, 1
	v_mov_b32_e32 v2, s0
	s_waitcnt vmcnt(0) lgkmcnt(0)
	global_atomic_add v4, v2, v0, s[6:7] offset:-128 sc0
	v_add_u32_e32 v1, 1, v1
	ds_write_b32 v145, v1 offset:40968
	v_mul_lo_u32 v6, v6, v1
	v_mul_lo_u32 v7, v7, v1
	s_waitcnt vmcnt(0)
	v_add_u32_e32 v4, 1, v4
	v_cmp_eq_u32_e32 vcc, v4, v6
	s_cbranch_vccz .Lfb8_poll
	buffer_wbl2 sc1
	s_waitcnt vmcnt(0)
	global_atomic_add v145, v0, s[6:7] offset:3968

; __device__ __forceinline__ unsigned xb_ld(unsigned* p)              { return __hip_atomic_load(p, __ATOMIC_RELAXED, __HIP_MEMORY_SCOPE_AGENT); }
; __device__ __forceinline__ unsigned xb_add(unsigned* p, unsigned v) { return __hip_atomic_fetch_add(p, v, __ATOMIC_RELAXED, __HIP_MEMORY_SCOPE_AGENT); }
; #define XB_SPIN(cond, bar) do { unsigned _sp = 0; while (cond) { __builtin_amdgcn_s_sleep(1); \
;     if ((++_sp & 255u) == 0u) { if (xb_ld(&(bar)[XB_TMO])) break; if (_sp > XB_SPIN_CAP) { atomicAdd(&(bar)[XB_TMO], 1u); break; } } } } while (0)
; __device__ __forceinline__ void xcd_barrier(const XcdBarrier& b) {
;   asm volatile("s_waitcnt vmcnt(0)" ::: "memory");
;   __syncthreads();
;   if (threadIdx.x == 0) {
;     unsigned* bar = b.bar;
;     __builtin_amdgcn_s_waitcnt(0);
;     unsigned nloc = b.st[0], nx = b.st[1];
;     if (nloc == 0u) { xcd_barrier_complete(bar, b.x, nloc, nx); b.st[0] = nloc; b.st[1] = nx; }
;     const unsigned old = xb_add(&bar[XB_XSUB(b.x)], 1u);
;     const unsigned gen = old / nloc;
;     if (old + 1u == (gen + 1u) * nloc) {
;       __builtin_amdgcn_fence(__ATOMIC_RELEASE, "agent");
;       asm volatile("s_waitcnt vmcnt(0)" ::: "memory");
;       const unsigned og = xb_add(&bar[XB_TOP], 1u);
;       const unsigned tg = og / nx;
;       if (og + 1u == (tg + 1u) * nx) xb_add(&bar[XB_TOPGEN], 1u);
;       else XB_SPIN(xb_ld(&bar[XB_TOPGEN]) == tg, bar);
;       __builtin_amdgcn_fence(__ATOMIC_ACQUIRE, "agent");
;       xb_add(&bar[XB_XGEN(b.x)], 1u);
;       asm volatile("s_waitcnt vmcnt(0)" ::: "memory");
;     } else {
;       XB_SPIN(xb_ld(&bar[XB_XGEN(b.x)]) == gen, bar);
;       __builtin_amdgcn_fence(__ATOMIC_ACQUIRE, "agent");
;       asm volatile("s_waitcnt vmcnt(0)" ::: "memory");
;     }
;   }
;   __syncthreads();
; }
.Lfb8_out:
	buffer_inv sc1
	s_waitcnt vmcnt(0) lgkmcnt(0)
	s_mov_b64 exec, s[12:13]
.Lfb8_done:
	s_and_saveexec_b64 s[20:21], s[38:39]
	s_branch .LBB0_1127
	s_waitcnt vmcnt(0) expcnt(0) lgkmcnt(0)
	ds_read_b32 v2, v145 offset:40960
	ds_read_b32 v0, v145 offset:40964
	s_waitcnt lgkmcnt(1)
	v_cmp_ne_u32_e32 vcc, 0, v2
	s_cbranch_vccnz .LBB0_1091
	s_mov_b32 s2, 1
	s_branch .LBB0_1079
